# v59 + P7 (ffnconv, VALU-issue bound) instruction trims: -2log2e folded into the GELU polynomial constants, conv bias folded into the first packed product (128 fewer VALU per 64 outputs)
# baseline (speedup 1.0000x reference)
; __device__ __forceinline__ unsigned cvt_pk_bf16(float lo, float hi) { unsigned r; asm volatile("v_cvt_pk_bf16_f32 %0, %1, %2" : "=v"(r) : "v"(lo), "v"(hi)); return r; }
; __device__ __forceinline__ float gelu_tanh(float x) {
;     const float u = x * (0.7978845608028654f + 0.035677408136300125f * x * x);
;     return x * __builtin_amdgcn_rcpf(1.0f + __builtin_amdgcn_exp2f(-2.0f * LOG2E * u));
; }
; __device__ __forceinline__ void ffnconv_phase(const bf16* h, bf16* gout, const float* cw, const float* cb, int T, int vcu, int NT) {
;     ...
;             for (int q = 0; q < RS; ++q) {
;                 const int tpos = (t + q) & (T - 1);
;                 const float mp = tpos == 0 ? 0.f : 1.f, mn = tpos == T - 1 ? 0.f : 1.f;
;                 float a0[8], a1[8], a2[8], b0[8], b1[8], b2[8], r[8];
;                 unpack8(gp_, a0); unpack8(gc_, a1); unpack8(gn_[q], a2); unpack8(vp_, b0); unpack8(vc_, b1); unpack8(vn_[q], b2);
; #pragma unroll
;                 for (int e = 0; e < 8; ++e) { const float hg = wg0[e] * (a0[e] * mp) + wg1[e] * a1[e] + wg2[e] * (a2[e] * mn) + bg[e];
;                     const float hv = wv0[e] * (b0[e] * mp) + wv1[e] * b1[e] + wv2[e] * (b2[e] * mn) + bv[e]; r[e] = gelu_tanh(hg) * hv; }
;                 v4u o; o.x = cvt_pk_bf16(r[0], r[1]); o.y = cvt_pk_bf16(r[2], r[3]); o.z = cvt_pk_bf16(r[4], r[5]); o.w = cvt_pk_bf16(r[6], r[7]);
;                 *(v4u*)(gout + (size_t)(t + q) * DFF + ch) = o;
;                 gp_ = gc_; gc_ = gn_[q]; vp_ = vc_; vc_ = vn_[q]; }
.LBB0_881:
	s_or_b64 exec, exec, s[24:25]
	v_add_u32_e32 v2, -7, v212
	v_and_b32_e32 v2, s88, v2
	v_cmp_eq_u32_e32 vcc, 0, v2
	s_waitcnt vmcnt(1)
	v_lshlrev_b32_e32 v193, 16, v96
	s_waitcnt vmcnt(0)
	v_lshlrev_b32_e32 v192, 16, v100
	v_cndmask_b32_e64 v206, 1.0, 0, vcc
	v_lshlrev_b32_e32 v197, 16, v88
	v_lshlrev_b32_e32 v196, 16, v92
	v_pk_mul_f32 v[192:193], v[206:207], v[192:193] op_sel_hi:[0,1]
	v_pk_fma_f32 v[194:195], v[148:149], v[196:197], v[144:145]
	v_lshlrev_b32_e32 v3, 16, v108
	v_lshlrev_b32_e32 v2, 16, v112
	v_pk_fma_f32 v[192:193], v[146:147], v[192:193], v[194:195]
	v_and_b32_e32 v195, 0xffff0000, v96
	v_pk_fma_f32 v[192:193], v[150:151], v[2:3], v[192:193]
	v_and_b32_e32 v199, 0xffff0000, v88
	v_and_b32_e32 v198, 0xffff0000, v92
	v_mul_f32_e32 v194, 0xbdd2d3e7, v193
	v_fmaak_f32 v194, v193, v194, 0xc0135761
	v_mul_f32_e32 v194, v193, v194
	v_exp_f32_e32 v194, v194
	v_pk_fma_f32 v[200:201], v[16:17], v[198:199], v[32:33]
	v_lshlrev_b32_e32 v202, 16, v101
	v_lshlrev_b32_e32 v203, 16, v97
	v_add_f32_e32 v194, 1.0, v194
	v_rcp_f32_e32 v194, v194
	v_pk_mul_f32 v[202:203], v[206:207], v[202:203] op_sel_hi:[0,1]
	v_and_b32_e32 v97, 0xffff0000, v97
	v_and_b32_e32 v96, 0xffff0000, v101
	v_mul_f32_e32 v193, v193, v194
	v_and_b32_e32 v194, 0xffff0000, v100
	v_pk_mul_f32 v[194:195], v[206:207], v[194:195] op_sel_hi:[0,1]
	v_mul_f32_e32 v220, v192, v193
	v_and_b32_e32 v193, 0xffff0000, v108
	v_and_b32_e32 v192, 0xffff0000, v112
	v_pk_fma_f32 v[194:195], v[8:9], v[194:195], v[200:201]
	v_lshlrev_b32_e32 v201, 16, v89
	v_pk_fma_f32 v[194:195], v[24:25], v[192:193], v[194:195]
	v_lshlrev_b32_e32 v200, 16, v93
	v_pk_fma_f32 v[204:205], v[140:141], v[200:201], v[136:137]
	v_mul_f32_e32 v88, 0xbdd2d3e7, v195
	v_fmaak_f32 v88, v195, v88, 0xc0135761
	v_mul_f32_e32 v88, v195, v88
	v_exp_f32_e32 v88, v88
	v_pk_fma_f32 v[202:203], v[138:139], v[202:203], v[204:205]
	v_lshlrev_b32_e32 v108, 16, v94
	v_and_b32_e32 v112, 0xffff0000, v94
	v_add_f32_e32 v88, 1.0, v88
	v_rcp_f32_e32 v88, v88
	v_lshlrev_b32_e32 v208, 16, v103
	v_lshlrev_b32_e32 v209, 16, v99
	v_pk_mul_f32 v[208:209], v[206:207], v[208:209] op_sel_hi:[0,1]
	v_mul_f32_e32 v88, v195, v88
	v_mul_f32_e32 v221, v194, v88
	v_lshlrev_b32_e32 v194, 16, v113
	v_lshlrev_b32_e32 v195, 16, v109
	v_pk_fma_f32 v[202:203], v[142:143], v[194:195], v[202:203]
	v_and_b32_e32 v99, 0xffff0000, v99
	v_add_u32_e32 v217, -6, v211
	v_mul_f32_e32 v88, 0xbdd2d3e7, v203
	v_fmaak_f32 v88, v203, v88, 0xc0135761
	v_mul_f32_e32 v88, v203, v88
	v_exp_f32_e32 v88, v88
	v_add_u32_e32 v216, -5, v211
	v_add_u32_e32 v215, -4, v211
	v_add_u32_e32 v214, -3, v211
	v_add_f32_e32 v88, 1.0, v88
	v_rcp_f32_e32 v88, v88
	v_add_u32_e32 v213, -2, v211
	v_add_u32_e32 v1, -1, v211
	v_lshl_add_u64 v[152:153], v[152:153], 0, s[16:17]
	v_mul_f32_e32 v88, v203, v88
	v_mul_f32_e32 v225, v202, v88
	v_and_b32_e32 v203, 0xffff0000, v89
	v_and_b32_e32 v202, 0xffff0000, v93
	v_pk_mul_f32 v[92:93], v[206:207], v[96:97] op_sel_hi:[0,1]
	v_pk_fma_f32 v[96:97], v[18:19], v[202:203], v[34:35]
	v_and_b32_e32 v89, 0xffff0000, v109
	v_and_b32_e32 v88, 0xffff0000, v113
	v_pk_fma_f32 v[92:93], v[10:11], v[92:93], v[96:97]
	v_lshlrev_b32_e32 v97, 16, v98
	v_pk_fma_f32 v[92:93], v[26:27], v[88:89], v[92:93]
	v_lshlrev_b32_e32 v109, 16, v90
	v_pk_fma_f32 v[100:101], v[132:133], v[108:109], v[128:129]
	v_mul_f32_e32 v96, 0xbdd2d3e7, v93
	v_fmaak_f32 v96, v93, v96, 0xc0135761
	v_mul_f32_e32 v96, v93, v96
	v_exp_f32_e32 v96, v96
	v_and_b32_e32 v113, 0xffff0000, v90
	v_pk_fma_f32 v[204:205], v[12:13], v[112:113], v[28:29]
	v_lshl_add_u64 v[154:155], v[154:155], 0, s[16:17]
	v_add_f32_e32 v96, 1.0, v96
	v_rcp_f32_e32 v96, v96
	v_lshl_add_u64 v[156:157], v[156:157], 0, s[16:17]
	v_lshl_add_u64 v[158:159], v[158:159], 0, s[16:17]
	v_lshl_add_u64 v[160:161], v[160:161], 0, s[16:17]
	v_mul_f32_e32 v93, v93, v96
	v_lshlrev_b32_e32 v96, 16, v102
	v_pk_mul_f32 v[96:97], v[206:207], v[96:97] op_sel_hi:[0,1]
	v_mul_f32_e32 v226, v92, v93
	v_lshlrev_b32_e32 v93, 16, v110
	v_lshlrev_b32_e32 v92, 16, v114
	v_pk_fma_f32 v[96:97], v[130:131], v[96:97], v[100:101]
	v_and_b32_e32 v101, 0xffff0000, v98
	v_pk_fma_f32 v[96:97], v[134:135], v[92:93], v[96:97]
	v_and_b32_e32 v98, 0xffff0000, v103
	v_lshlrev_b32_e32 v103, 16, v84
	v_mul_f32_e32 v100, 0xbdd2d3e7, v97
	v_fmaak_f32 v100, v97, v100, 0xc0135761
	v_mul_f32_e32 v100, v97, v100
	v_exp_f32_e32 v100, v100
	v_lshl_add_u64 v[162:163], v[162:163], 0, s[16:17]
	v_lshl_add_u64 v[164:165], v[164:165], 0, s[16:17]
	v_lshl_add_u64 v[166:167], v[166:167], 0, s[16:17]
	v_add_f32_e32 v100, 1.0, v100
	v_rcp_f32_e32 v100, v100
	v_lshl_add_u64 v[168:169], v[168:169], 0, s[16:17]
	v_lshl_add_u64 v[170:171], v[170:171], 0, s[16:17]
	v_lshl_add_u64 v[172:173], v[172:173], 0, s[16:17]
	v_mul_f32_e32 v97, v97, v100
	v_and_b32_e32 v100, 0xffff0000, v102
	v_pk_mul_f32 v[100:101], v[206:207], v[100:101] op_sel_hi:[0,1]
	v_mul_f32_e32 v227, v96, v97
	v_and_b32_e32 v97, 0xffff0000, v110
	v_and_b32_e32 v96, 0xffff0000, v114
	v_pk_fma_f32 v[100:101], v[4:5], v[100:101], v[204:205]
	v_lshlrev_b32_e32 v205, 16, v91
	v_pk_fma_f32 v[100:101], v[20:21], v[96:97], v[100:101]
	v_lshlrev_b32_e32 v204, 16, v95
	v_pk_fma_f32 v[218:219], v[124:125], v[204:205], v[120:121]
	v_mul_f32_e32 v90, 0xbdd2d3e7, v101
	v_fmaak_f32 v90, v101, v90, 0xc0135761
	v_mul_f32_e32 v90, v101, v90
	v_exp_f32_e32 v90, v90
	v_pk_fma_f32 v[208:209], v[122:123], v[208:209], v[218:219]
	v_cvt_pk_bf16_f32 v218, v220, v221
	v_cvt_pk_bf16_f32 v219, v225, v226
	v_add_f32_e32 v90, 1.0, v90
	v_rcp_f32_e32 v90, v90
	v_lshlrev_b32_e32 v114, 16, v107
	v_lshl_add_u64 v[174:175], v[174:175], 0, s[16:17]
; __device__ __forceinline__ unsigned cvt_pk_bf16(float lo, float hi) { unsigned r; asm volatile("v_cvt_pk_bf16_f32 %0, %1, %2" : "=v"(r) : "v"(lo), "v"(hi)); return r; }
; __device__ __forceinline__ float gelu_tanh(float x) {
;     const float u = x * (0.7978845608028654f + 0.035677408136300125f * x * x);
;     return x * __builtin_amdgcn_rcpf(1.0f + __builtin_amdgcn_exp2f(-2.0f * LOG2E * u));
; }
; __device__ __forceinline__ void ffnconv_phase(const bf16* h, bf16* gout, const float* cw, const float* cb, int T, int vcu, int NT) {
;     ...
;             for (int q = 0; q < RS; ++q) {
;                 const int tpos = (t + q) & (T - 1);
;                 const float mp = tpos == 0 ? 0.f : 1.f, mn = tpos == T - 1 ? 0.f : 1.f;
;                 float a0[8], a1[8], a2[8], b0[8], b1[8], b2[8], r[8];
;                 unpack8(gp_, a0); unpack8(gc_, a1); unpack8(gn_[q], a2); unpack8(vp_, b0); unpack8(vc_, b1); unpack8(vn_[q], b2);
; #pragma unroll
;                 for (int e = 0; e < 8; ++e) { const float hg = wg0[e] * (a0[e] * mp) + wg1[e] * a1[e] + wg2[e] * (a2[e] * mn) + bg[e];
;                     const float hv = wv0[e] * (b0[e] * mp) + wv1[e] * b1[e] + wv2[e] * (b2[e] * mn) + bv[e]; r[e] = gelu_tanh(hg) * hv; }
;                 v4u o; o.x = cvt_pk_bf16(r[0], r[1]); o.y = cvt_pk_bf16(r[2], r[3]); o.z = cvt_pk_bf16(r[4], r[5]); o.w = cvt_pk_bf16(r[6], r[7]);
;                 *(v4u*)(gout + (size_t)(t + q) * DFF + ch) = o;
;                 gp_ = gc_; gc_ = gn_[q]; vp_ = vc_; vc_ = vn_[q]; }
	v_lshl_add_u64 v[176:177], v[176:177], 0, s[16:17]
	v_mul_f32_e32 v90, v101, v90
	v_mul_f32_e32 v102, v100, v90
	v_lshlrev_b32_e32 v100, 16, v115
	v_lshlrev_b32_e32 v101, 16, v111
	v_pk_fma_f32 v[208:209], v[126:127], v[100:101], v[208:209]
	v_cvt_pk_bf16_f32 v220, v227, v102
	v_lshlrev_b32_e32 v102, 16, v104
	v_lshl_add_u64 v[178:179], v[178:179], 0, s[16:17]
	v_mul_f32_e32 v90, 0xbdd2d3e7, v209
	v_fmaak_f32 v90, v209, v90, 0xc0135761
	v_mul_f32_e32 v90, v209, v90
	v_exp_f32_e32 v90, v90
	v_lshl_add_u64 v[186:187], v[186:187], 0, s[16:17]
	v_lshl_add_u64 v[188:189], v[188:189], 0, s[16:17]
	v_add_f32_e32 v90, 1.0, v90
	v_rcp_f32_e32 v90, v90
	s_nop 0
	v_mul_f32_e32 v90, v209, v90
	v_mul_f32_e32 v110, v208, v90
	v_and_b32_e32 v209, 0xffff0000, v91
	v_and_b32_e32 v208, 0xffff0000, v95
	v_pk_mul_f32 v[94:95], v[206:207], v[98:99] op_sel_hi:[0,1]
	v_pk_fma_f32 v[98:99], v[14:15], v[208:209], v[30:31]
	v_and_b32_e32 v91, 0xffff0000, v111
	v_and_b32_e32 v90, 0xffff0000, v115
	v_pk_fma_f32 v[94:95], v[6:7], v[94:95], v[98:99]
	v_lshlrev_b32_e32 v115, 16, v87
	v_pk_fma_f32 v[94:95], v[22:23], v[90:91], v[94:95]
	v_and_b32_e32 v87, 0xffff0000, v87
	s_nop 0
	v_mul_f32_e32 v98, 0xbdd2d3e7, v95
	v_fmaak_f32 v98, v95, v98, 0xc0135761
	v_mul_f32_e32 v98, v95, v98
	v_exp_f32_e32 v98, v98
	s_nop 0
	v_add_f32_e32 v98, 1.0, v98
	v_rcp_f32_e32 v98, v98
	s_nop 0
	v_mul_f32_e32 v95, v95, v98
	v_mul_f32_e32 v94, v94, v95
	v_cvt_pk_bf16_f32 v221, v110, v94
	v_lshl_add_u64 v[94:95], v[190:191], 0, v[116:117]
	global_store_dwordx4 v[94:95], v[218:221], off
	v_pk_fma_f32 v[94:95], v[148:149], v[2:3], v[144:145]
	s_nop 0
	v_pk_fma_f32 v[94:95], v[146:147], v[196:197], v[94:95]
	v_lshlrev_b32_e32 v197, 16, v86
	v_pk_fma_f32 v[94:95], v[150:151], v[102:103], v[94:95]
	v_lshlrev_b32_e32 v196, 16, v106
	s_nop 0
	v_mul_f32_e32 v98, 0xbdd2d3e7, v95
	v_fmaak_f32 v98, v95, v98, 0xc0135761
	v_mul_f32_e32 v98, v95, v98
	v_exp_f32_e32 v98, v98
	s_nop 0
	v_add_f32_e32 v98, 1.0, v98
	v_rcp_f32_e32 v98, v98
	s_nop 0
	v_mul_f32_e32 v95, v95, v98
	v_pk_fma_f32 v[98:99], v[16:17], v[192:193], v[32:33]
	v_mul_f32_e32 v110, v94, v95
	v_and_b32_e32 v95, 0xffff0000, v84
	v_and_b32_e32 v94, 0xffff0000, v104
	v_pk_fma_f32 v[98:99], v[8:9], v[198:199], v[98:99]
	v_lshlrev_b32_e32 v198, 16, v105
	v_pk_fma_f32 v[98:99], v[24:25], v[94:95], v[98:99]
	v_lshlrev_b32_e32 v199, 16, v85
	v_and_b32_e32 v85, 0xffff0000, v85
	v_mul_f32_e32 v84, 0xbdd2d3e7, v99
	v_fmaak_f32 v84, v99, v84, 0xc0135761
	v_mul_f32_e32 v84, v99, v84
	v_exp_f32_e32 v84, v84
	s_nop 0
	v_add_f32_e32 v84, 1.0, v84
	v_rcp_f32_e32 v84, v84
	s_nop 0
	v_mul_f32_e32 v84, v99, v84
	v_mul_f32_e32 v111, v98, v84
	v_pk_fma_f32 v[98:99], v[140:141], v[194:195], v[136:137]
	s_nop 0
	v_pk_fma_f32 v[98:99], v[138:139], v[200:201], v[98:99]
	s_nop 0
	v_pk_fma_f32 v[98:99], v[142:143], v[198:199], v[98:99]
	s_nop 0
	s_nop 0
	v_mul_f32_e32 v84, 0xbdd2d3e7, v99
	v_fmaak_f32 v84, v99, v84, 0xc0135761
	v_mul_f32_e32 v84, v99, v84
	v_exp_f32_e32 v84, v84
	s_nop 0
	v_add_f32_e32 v84, 1.0, v84
	v_rcp_f32_e32 v84, v84
	s_nop 0
	v_mul_f32_e32 v84, v99, v84
	v_mul_f32_e32 v200, v98, v84
	v_pk_fma_f32 v[98:99], v[18:19], v[88:89], v[34:35]
	v_and_b32_e32 v84, 0xffff0000, v105
	v_pk_fma_f32 v[98:99], v[10:11], v[202:203], v[98:99]
	s_nop 0
	v_pk_fma_f32 v[98:99], v[26:27], v[84:85], v[98:99]
	s_nop 0
	s_nop 0
	v_mul_f32_e32 v104, 0xbdd2d3e7, v99
	v_fmaak_f32 v104, v99, v104, 0xc0135761
	v_mul_f32_e32 v104, v99, v104
	v_exp_f32_e32 v104, v104
	s_nop 0
	v_add_f32_e32 v104, 1.0, v104
	v_rcp_f32_e32 v104, v104
	s_nop 0
	v_mul_f32_e32 v99, v99, v104
	v_mul_f32_e32 v201, v98, v99
	v_pk_fma_f32 v[98:99], v[132:133], v[92:93], v[128:129]
	s_nop 0
	v_pk_fma_f32 v[98:99], v[130:131], v[108:109], v[98:99]
	s_nop 0
	v_pk_fma_f32 v[98:99], v[134:135], v[196:197], v[98:99]
	s_nop 0
	s_nop 0
	v_mul_f32_e32 v104, 0xbdd2d3e7, v99
	v_fmaak_f32 v104, v99, v104, 0xc0135761
	v_mul_f32_e32 v104, v99, v104
	v_exp_f32_e32 v104, v104
	s_nop 0
	v_add_f32_e32 v104, 1.0, v104
	v_rcp_f32_e32 v104, v104
	s_nop 0
	v_mul_f32_e32 v99, v99, v104
	v_pk_fma_f32 v[104:105], v[12:13], v[96:97], v[28:29]
	v_mul_f32_e32 v108, v98, v99
	v_and_b32_e32 v99, 0xffff0000, v86
	v_and_b32_e32 v98, 0xffff0000, v106
	v_pk_fma_f32 v[104:105], v[4:5], v[112:113], v[104:105]
	v_lshlrev_b32_e32 v113, 16, v76
	v_pk_fma_f32 v[104:105], v[20:21], v[98:99], v[104:105]
	v_lshlrev_b32_e32 v112, 16, v80
	s_nop 0
	v_mul_f32_e32 v86, 0xbdd2d3e7, v105
	v_fmaak_f32 v86, v105, v86, 0xc0135761
	v_mul_f32_e32 v86, v105, v86
	v_exp_f32_e32 v86, v86
	s_nop 0
	v_add_f32_e32 v86, 1.0, v86
	v_rcp_f32_e32 v86, v86
	s_nop 0
	v_mul_f32_e32 v86, v105, v86
	v_mul_f32_e32 v106, v104, v86
	v_pk_fma_f32 v[104:105], v[124:125], v[100:101], v[120:121]
	s_nop 0
	v_pk_fma_f32 v[104:105], v[122:123], v[204:205], v[104:105]
	s_nop 0
	v_pk_fma_f32 v[104:105], v[126:127], v[114:115], v[104:105]
	s_nop 0
	s_nop 0
	v_mul_f32_e32 v86, 0xbdd2d3e7, v105
	v_fmaak_f32 v86, v105, v86, 0xc0135761
	v_mul_f32_e32 v86, v105, v86
	v_exp_f32_e32 v86, v86
	s_nop 0
	v_add_f32_e32 v86, 1.0, v86
	v_rcp_f32_e32 v86, v86
	s_nop 0
	v_mul_f32_e32 v86, v105, v86
	v_mul_f32_e32 v109, v104, v86
	v_pk_fma_f32 v[104:105], v[14:15], v[90:91], v[30:31]
	v_and_b32_e32 v86, 0xffff0000, v107
	v_pk_fma_f32 v[104:105], v[6:7], v[208:209], v[104:105]
	s_nop 0
	v_pk_fma_f32 v[104:105], v[22:23], v[86:87], v[104:105]
	s_nop 0
	s_nop 0
	v_mul_f32_e32 v107, 0xbdd2d3e7, v105
	v_fmaak_f32 v107, v105, v107, 0xc0135761
	v_mul_f32_e32 v107, v105, v107
	v_exp_f32_e32 v107, v107
	s_nop 0
	v_add_f32_e32 v107, 1.0, v107
	v_rcp_f32_e32 v107, v107
	s_nop 0
	v_mul_f32_e32 v105, v105, v107
; __device__ __forceinline__ unsigned cvt_pk_bf16(float lo, float hi) { unsigned r; asm volatile("v_cvt_pk_bf16_f32 %0, %1, %2" : "=v"(r) : "v"(lo), "v"(hi)); return r; }
; __device__ __forceinline__ void ffnconv_phase(const bf16* h, bf16* gout, const float* cw, const float* cb, int T, int vcu, int NT) {
;     ...
;             for (int q = 0; q < RS; ++q) {
;                 const int tpos = (t + q) & (T - 1);
;                 const float mp = tpos == 0 ? 0.f : 1.f, mn = tpos == T - 1 ? 0.f : 1.f;
;                 float a0[8], a1[8], a2[8], b0[8], b1[8], b2[8], r[8];
;                 unpack8(gp_, a0); unpack8(gc_, a1); unpack8(gn_[q], a2); unpack8(vp_, b0); unpack8(vc_, b1); unpack8(vn_[q], b2);
; #pragma unroll
;                 for (int e = 0; e < 8; ++e) { const float hg = wg0[e] * (a0[e] * mp) + wg1[e] * a1[e] + wg2[e] * (a2[e] * mn) + bg[e];
;                     const float hv = wv0[e] * (b0[e] * mp) + wv1[e] * b1[e] + wv2[e] * (b2[e] * mn) + bv[e]; r[e] = gelu_tanh(hg) * hv; }
;                 v4u o; o.x = cvt_pk_bf16(r[0], r[1]); o.y = cvt_pk_bf16(r[2], r[3]); o.z = cvt_pk_bf16(r[4], r[5]); o.w = cvt_pk_bf16(r[6], r[7]);
;                 *(v4u*)(gout + (size_t)(t + q) * DFF + ch) = o;
	v_mul_f32_e32 v107, v104, v105
	v_cvt_pk_bf16_f32 v104, v110, v111
	v_cvt_pk_bf16_f32 v105, v200, v201
	v_cvt_pk_bf16_f32 v106, v108, v106
	v_cvt_pk_bf16_f32 v107, v109, v107
	v_mad_i64_i32 v[108:109], s[24:25], v217, s84, v[118:119]
	global_store_dwordx4 v[108:109], v[104:107], off
	v_lshlrev_b32_e32 v110, 16, v81
	v_lshlrev_b32_e32 v111, 16, v77
	v_pk_fma_f32 v[104:105], v[148:149], v[102:103], v[144:145]
	v_and_b32_e32 v77, 0xffff0000, v77
	v_pk_fma_f32 v[2:3], v[146:147], v[2:3], v[104:105]
	v_lshlrev_b32_e32 v109, 16, v78
	v_pk_fma_f32 v[2:3], v[150:151], v[112:113], v[2:3]
	v_lshlrev_b32_e32 v108, 16, v82
	v_lshlrev_b32_e32 v106, 16, v83
	v_mul_f32_e32 v104, 0xbdd2d3e7, v3
	v_fmaak_f32 v104, v3, v104, 0xc0135761
	v_mul_f32_e32 v104, v3, v104
	v_exp_f32_e32 v104, v104
	v_lshlrev_b32_e32 v107, 16, v79
	v_and_b32_e32 v79, 0xffff0000, v79
	v_add_f32_e32 v104, 1.0, v104
	v_rcp_f32_e32 v104, v104
	s_nop 0
	v_mul_f32_e32 v3, v3, v104
	v_pk_fma_f32 v[104:105], v[16:17], v[94:95], v[32:33]
	v_mul_f32_e32 v200, v2, v3
	v_and_b32_e32 v3, 0xffff0000, v76
	v_and_b32_e32 v2, 0xffff0000, v80
	v_pk_fma_f32 v[104:105], v[8:9], v[192:193], v[104:105]
	s_nop 0
	v_pk_fma_f32 v[104:105], v[24:25], v[2:3], v[104:105]
	s_nop 0
	s_nop 0
	v_mul_f32_e32 v76, 0xbdd2d3e7, v105
	v_fmaak_f32 v76, v105, v76, 0xc0135761
	v_mul_f32_e32 v76, v105, v76
	v_exp_f32_e32 v76, v76
	s_nop 0
	v_add_f32_e32 v76, 1.0, v76
	v_rcp_f32_e32 v76, v76
	s_nop 0
	v_mul_f32_e32 v76, v105, v76
	v_mul_f32_e32 v192, v104, v76
	v_pk_fma_f32 v[104:105], v[140:141], v[198:199], v[136:137]
	s_nop 0
	v_pk_fma_f32 v[104:105], v[138:139], v[194:195], v[104:105]
	s_nop 0
	v_pk_fma_f32 v[104:105], v[142:143], v[110:111], v[104:105]
	s_nop 0
	s_nop 0
	v_mul_f32_e32 v76, 0xbdd2d3e7, v105
	v_fmaak_f32 v76, v105, v76, 0xc0135761
	v_mul_f32_e32 v76, v105, v76
	v_exp_f32_e32 v76, v76
	s_nop 0
	v_add_f32_e32 v76, 1.0, v76
	v_rcp_f32_e32 v76, v76
	s_nop 0
	v_mul_f32_e32 v76, v105, v76
	v_mul_f32_e32 v104, v104, v76
	v_and_b32_e32 v76, 0xffff0000, v81
	v_pk_fma_f32 v[80:81], v[18:19], v[84:85], v[34:35]
	s_nop 0
	v_pk_fma_f32 v[80:81], v[10:11], v[88:89], v[80:81]
	s_nop 0
	v_pk_fma_f32 v[80:81], v[26:27], v[76:77], v[80:81]
	s_nop 0
	s_nop 0
	v_mul_f32_e32 v88, 0xbdd2d3e7, v81
	v_fmaak_f32 v88, v81, v88, 0xc0135761
	v_mul_f32_e32 v88, v81, v88
	v_exp_f32_e32 v88, v88
	s_nop 0
	v_add_f32_e32 v88, 1.0, v88
	v_rcp_f32_e32 v88, v88
	s_nop 0
	v_mul_f32_e32 v81, v81, v88
	v_mul_f32_e32 v105, v80, v81
	v_pk_fma_f32 v[80:81], v[132:133], v[196:197], v[128:129]
	s_nop 0
	v_pk_fma_f32 v[80:81], v[130:131], v[92:93], v[80:81]
	s_nop 0
	v_pk_fma_f32 v[80:81], v[134:135], v[108:109], v[80:81]
	s_nop 0
	s_nop 0
	v_mul_f32_e32 v88, 0xbdd2d3e7, v81
	v_fmaak_f32 v88, v81, v88, 0xc0135761
	v_mul_f32_e32 v88, v81, v88
	v_exp_f32_e32 v88, v88
	s_nop 0
	v_add_f32_e32 v88, 1.0, v88
	v_rcp_f32_e32 v88, v88
	s_nop 0
	v_mul_f32_e32 v81, v81, v88
	v_pk_fma_f32 v[88:89], v[12:13], v[98:99], v[28:29]
	v_mul_f32_e32 v92, v80, v81
	v_and_b32_e32 v81, 0xffff0000, v78
	v_and_b32_e32 v80, 0xffff0000, v82
	v_pk_fma_f32 v[88:89], v[4:5], v[96:97], v[88:89]
	v_lshlrev_b32_e32 v97, 16, v71
	v_pk_fma_f32 v[88:89], v[20:21], v[80:81], v[88:89]
	v_and_b32_e32 v71, 0xffff0000, v71
	s_nop 0
	v_mul_f32_e32 v78, 0xbdd2d3e7, v89
	v_fmaak_f32 v78, v89, v78, 0xc0135761
	v_mul_f32_e32 v78, v89, v78
	v_exp_f32_e32 v78, v78
	s_nop 0
	v_add_f32_e32 v78, 1.0, v78
	v_rcp_f32_e32 v78, v78
	s_nop 0
	v_mul_f32_e32 v78, v89, v78
	v_mul_f32_e32 v93, v88, v78
	v_pk_fma_f32 v[88:89], v[124:125], v[114:115], v[120:121]
	s_nop 0
	v_pk_fma_f32 v[88:89], v[122:123], v[100:101], v[88:89]
	v_lshlrev_b32_e32 v101, 16, v70
	v_pk_fma_f32 v[88:89], v[126:127], v[106:107], v[88:89]
	v_lshlrev_b32_e32 v100, 16, v74
	s_nop 0
	v_mul_f32_e32 v78, 0xbdd2d3e7, v89
	v_fmaak_f32 v78, v89, v78, 0xc0135761
	v_mul_f32_e32 v78, v89, v78
	v_exp_f32_e32 v78, v78
	s_nop 0
	v_add_f32_e32 v78, 1.0, v78
	v_rcp_f32_e32 v78, v78
	s_nop 0
	v_mul_f32_e32 v78, v89, v78
	v_mul_f32_e32 v96, v88, v78
	v_and_b32_e32 v78, 0xffff0000, v83
	v_pk_fma_f32 v[82:83], v[14:15], v[86:87], v[30:31]
	s_nop 0
	v_pk_fma_f32 v[82:83], v[6:7], v[90:91], v[82:83]
	s_nop 0
	v_pk_fma_f32 v[82:83], v[22:23], v[78:79], v[82:83]
	s_nop 0
	s_nop 0
	v_mul_f32_e32 v88, 0xbdd2d3e7, v83
	v_fmaak_f32 v88, v83, v88, 0xc0135761
	v_mul_f32_e32 v88, v83, v88
	v_exp_f32_e32 v88, v88
	s_nop 0
	v_add_f32_e32 v88, 1.0, v88
	v_rcp_f32_e32 v88, v88
	s_nop 0
	v_mul_f32_e32 v83, v83, v88
	v_mul_f32_e32 v82, v82, v83
	v_cvt_pk_bf16_f32 v88, v200, v192
	v_cvt_pk_bf16_f32 v89, v104, v105
	v_cvt_pk_bf16_f32 v90, v92, v93
	v_cvt_pk_bf16_f32 v91, v96, v82
	v_mad_i64_i32 v[82:83], s[24:25], v216, s84, v[118:119]
	global_store_dwordx4 v[82:83], v[88:91], off
	v_pk_fma_f32 v[82:83], v[148:149], v[112:113], v[144:145]
	v_lshlrev_b32_e32 v105, 16, v68
	v_lshlrev_b32_e32 v104, 16, v72
	v_pk_fma_f32 v[82:83], v[146:147], v[102:103], v[82:83]
	v_lshlrev_b32_e32 v102, 16, v73
	v_pk_fma_f32 v[82:83], v[150:151], v[104:105], v[82:83]
	v_lshlrev_b32_e32 v103, 16, v69
	v_lshlrev_b32_e32 v96, 16, v75
	v_mul_f32_e32 v88, 0xbdd2d3e7, v83
	v_fmaak_f32 v88, v83, v88, 0xc0135761
	v_mul_f32_e32 v88, v83, v88
	v_exp_f32_e32 v88, v88
	s_nop 0
	v_add_f32_e32 v88, 1.0, v88
	v_rcp_f32_e32 v88, v88
	s_nop 0
	v_mul_f32_e32 v83, v83, v88
	v_pk_fma_f32 v[88:89], v[16:17], v[2:3], v[32:33]
	v_mul_f32_e32 v90, v82, v83
	v_and_b32_e32 v83, 0xffff0000, v68
	v_and_b32_e32 v82, 0xffff0000, v72
	v_pk_fma_f32 v[88:89], v[8:9], v[94:95], v[88:89]
	v_lshlrev_b32_e32 v95, 16, v60
	v_pk_fma_f32 v[88:89], v[24:25], v[82:83], v[88:89]
	s_nop 0
	s_nop 0
	v_mul_f32_e32 v68, 0xbdd2d3e7, v89
; __device__ __forceinline__ unsigned cvt_pk_bf16(float lo, float hi) { unsigned r; asm volatile("v_cvt_pk_bf16_f32 %0, %1, %2" : "=v"(r) : "v"(lo), "v"(hi)); return r; }
; __device__ __forceinline__ void ffnconv_phase(const bf16* h, bf16* gout, const float* cw, const float* cb, int T, int vcu, int NT) {
;     ...
;             for (int q = 0; q < RS; ++q) {
;                 const int tpos = (t + q) & (T - 1);
;                 const float mp = tpos == 0 ? 0.f : 1.f, mn = tpos == T - 1 ? 0.f : 1.f;
;                 float a0[8], a1[8], a2[8], b0[8], b1[8], b2[8], r[8];
;                 unpack8(gp_, a0); unpack8(gc_, a1); unpack8(gn_[q], a2); unpack8(vp_, b0); unpack8(vc_, b1); unpack8(vn_[q], b2);
; #pragma unroll
;                 for (int e = 0; e < 8; ++e) { const float hg = wg0[e] * (a0[e] * mp) + wg1[e] * a1[e] + wg2[e] * (a2[e] * mn) + bg[e];
;                     const float hv = wv0[e] * (b0[e] * mp) + wv1[e] * b1[e] + wv2[e] * (b2[e] * mn) + bv[e]; r[e] = gelu_tanh(hg) * hv; }
;                 v4u o; o.x = cvt_pk_bf16(r[0], r[1]); o.y = cvt_pk_bf16(r[2], r[3]); o.z = cvt_pk_bf16(r[4], r[5]); o.w = cvt_pk_bf16(r[6], r[7]);
;                 *(v4u*)(gout + (size_t)(t + q) * DFF + ch) = o;
	v_fmaak_f32 v68, v89, v68, 0xc0135761
	v_mul_f32_e32 v68, v89, v68
	v_exp_f32_e32 v68, v68
	s_nop 0
	v_add_f32_e32 v68, 1.0, v68
	v_rcp_f32_e32 v68, v68
	s_nop 0
	v_mul_f32_e32 v68, v89, v68
	v_mul_f32_e32 v91, v88, v68
	v_pk_fma_f32 v[88:89], v[140:141], v[110:111], v[136:137]
	s_nop 0
	v_pk_fma_f32 v[88:89], v[138:139], v[198:199], v[88:89]
	s_nop 0
	v_pk_fma_f32 v[88:89], v[142:143], v[102:103], v[88:89]
	s_nop 0
	s_nop 0
	v_mul_f32_e32 v68, 0xbdd2d3e7, v89
	v_fmaak_f32 v68, v89, v68, 0xc0135761
	v_mul_f32_e32 v68, v89, v68
	v_exp_f32_e32 v68, v68
	s_nop 0
	v_add_f32_e32 v68, 1.0, v68
	v_rcp_f32_e32 v68, v68
	s_nop 0
	v_mul_f32_e32 v68, v89, v68
	v_mul_f32_e32 v92, v88, v68
	v_and_b32_e32 v89, 0xffff0000, v69
	v_pk_fma_f32 v[68:69], v[18:19], v[76:77], v[34:35]
	v_and_b32_e32 v88, 0xffff0000, v73
	v_pk_fma_f32 v[68:69], v[10:11], v[84:85], v[68:69]
	v_and_b32_e32 v73, 0xffff0000, v70
	v_pk_fma_f32 v[68:69], v[26:27], v[88:89], v[68:69]
	v_cvt_pk_bf16_f32 v84, v90, v91
	v_lshlrev_b32_e32 v91, 16, v62
	v_lshlrev_b32_e32 v90, 16, v66
	v_mul_f32_e32 v72, 0xbdd2d3e7, v69
	v_fmaak_f32 v72, v69, v72, 0xc0135761
	v_mul_f32_e32 v72, v69, v72
	v_exp_f32_e32 v72, v72
	s_nop 0
	v_add_f32_e32 v72, 1.0, v72
	v_rcp_f32_e32 v72, v72
	s_nop 0
	v_mul_f32_e32 v69, v69, v72
	v_mul_f32_e32 v85, v68, v69
	v_pk_fma_f32 v[68:69], v[132:133], v[108:109], v[128:129]
	v_cvt_pk_bf16_f32 v85, v92, v85
	v_lshlrev_b32_e32 v92, 16, v65
	v_pk_fma_f32 v[68:69], v[130:131], v[196:197], v[68:69]
	s_nop 0
	v_pk_fma_f32 v[68:69], v[134:135], v[100:101], v[68:69]
	s_nop 0
	s_nop 0
	v_mul_f32_e32 v72, 0xbdd2d3e7, v69
	v_fmaak_f32 v72, v69, v72, 0xc0135761
	v_mul_f32_e32 v72, v69, v72
	v_exp_f32_e32 v72, v72
	s_nop 0
	v_add_f32_e32 v72, 1.0, v72
	v_rcp_f32_e32 v72, v72
	s_nop 0
	v_mul_f32_e32 v69, v69, v72
	v_mul_f32_e32 v93, v68, v69
	v_pk_fma_f32 v[68:69], v[12:13], v[80:81], v[28:29]
	v_and_b32_e32 v72, 0xffff0000, v74
	v_pk_fma_f32 v[68:69], v[4:5], v[98:99], v[68:69]
	v_mov_b32_e32 v99, v39
	v_pk_fma_f32 v[68:69], v[20:21], v[72:73], v[68:69]
	s_nop 0
	s_nop 0
	v_mul_f32_e32 v70, 0xbdd2d3e7, v69
	v_fmaak_f32 v70, v69, v70, 0xc0135761
	v_mul_f32_e32 v70, v69, v70
	v_exp_f32_e32 v70, v70
	s_nop 0
	v_add_f32_e32 v70, 1.0, v70
	v_rcp_f32_e32 v70, v70
	s_nop 0
	v_mul_f32_e32 v69, v69, v70
	v_mul_f32_e32 v74, v68, v69
	v_pk_fma_f32 v[68:69], v[124:125], v[106:107], v[120:121]
	s_nop 0
	v_pk_fma_f32 v[68:69], v[122:123], v[114:115], v[68:69]
	s_nop 0
	v_pk_fma_f32 v[68:69], v[126:127], v[96:97], v[68:69]
	s_nop 0
	s_nop 0
	v_mul_f32_e32 v70, 0xbdd2d3e7, v69
	v_fmaak_f32 v70, v69, v70, 0xc0135761
	v_mul_f32_e32 v70, v69, v70
	v_exp_f32_e32 v70, v70
	s_nop 0
	v_add_f32_e32 v70, 1.0, v70
	v_rcp_f32_e32 v70, v70
	s_nop 0
	v_mul_f32_e32 v69, v69, v70
	v_mul_f32_e32 v94, v68, v69
	v_pk_fma_f32 v[68:69], v[14:15], v[78:79], v[30:31]
	v_and_b32_e32 v70, 0xffff0000, v75
	v_pk_fma_f32 v[68:69], v[6:7], v[86:87], v[68:69]
	v_cvt_pk_bf16_f32 v86, v93, v74
	v_lshlrev_b32_e32 v93, 16, v61
	v_pk_fma_f32 v[68:69], v[22:23], v[70:71], v[68:69]
	s_nop 0
	s_nop 0
	v_mul_f32_e32 v75, 0xbdd2d3e7, v69
	v_fmaak_f32 v75, v69, v75, 0xc0135761
	v_mul_f32_e32 v75, v69, v75
	v_exp_f32_e32 v75, v75
	s_nop 0
	v_add_f32_e32 v75, 1.0, v75
	v_rcp_f32_e32 v75, v75
	s_nop 0
	v_mul_f32_e32 v69, v69, v75
	v_mul_f32_e32 v68, v68, v69
	v_cvt_pk_bf16_f32 v87, v94, v68
	v_mad_i64_i32 v[68:69], s[24:25], v215, s84, v[118:119]
	global_store_dwordx4 v[68:69], v[84:87], off
	v_pk_fma_f32 v[68:69], v[148:149], v[104:105], v[144:145]
	v_lshlrev_b32_e32 v94, 16, v64
	v_pk_fma_f32 v[68:69], v[146:147], v[112:113], v[68:69]
	v_and_b32_e32 v75, 0xffff0000, v60
	v_pk_fma_f32 v[68:69], v[150:151], v[94:95], v[68:69]
	v_and_b32_e32 v85, 0xffff0000, v61
	v_and_b32_e32 v84, 0xffff0000, v65
	v_mul_f32_e32 v74, 0xbdd2d3e7, v69
	v_fmaak_f32 v74, v69, v74, 0xc0135761
	v_mul_f32_e32 v74, v69, v74
	v_exp_f32_e32 v74, v74
	v_lshlrev_b32_e32 v86, 16, v67
	v_lshlrev_b32_e32 v87, 16, v63
	v_add_f32_e32 v74, 1.0, v74
	v_rcp_f32_e32 v74, v74
	s_nop 0
	v_mul_f32_e32 v69, v69, v74
	v_mul_f32_e32 v98, v68, v69
	v_pk_fma_f32 v[68:69], v[16:17], v[82:83], v[32:33]
	v_and_b32_e32 v74, 0xffff0000, v64
	v_pk_fma_f32 v[2:3], v[8:9], v[2:3], v[68:69]
	v_lshlrev_b32_e32 v69, 16, v52
	v_pk_fma_f32 v[2:3], v[24:25], v[74:75], v[2:3]
	v_lshlrev_b32_e32 v68, 16, v56
	s_nop 0
	v_mul_f32_e32 v60, 0xbdd2d3e7, v3
	v_fmaak_f32 v60, v3, v60, 0xc0135761
	v_mul_f32_e32 v60, v3, v60
	v_exp_f32_e32 v60, v60
	s_nop 0
	v_add_f32_e32 v60, 1.0, v60
	v_rcp_f32_e32 v60, v60
	s_nop 0
	v_mul_f32_e32 v3, v3, v60
	v_mul_f32_e32 v60, v2, v3
	v_pk_fma_f32 v[2:3], v[140:141], v[102:103], v[136:137]
	v_cvt_pk_bf16_f32 v60, v98, v60
	v_mov_b32_e32 v98, v38
	v_pk_fma_f32 v[2:3], v[138:139], v[110:111], v[2:3]
	s_nop 0
	v_pk_fma_f32 v[2:3], v[142:143], v[92:93], v[2:3]
	s_nop 0
	s_nop 0
	v_mul_f32_e32 v64, 0xbdd2d3e7, v3
	v_fmaak_f32 v64, v3, v64, 0xc0135761
	v_mul_f32_e32 v64, v3, v64
	v_exp_f32_e32 v64, v64
	s_nop 0
	v_add_f32_e32 v64, 1.0, v64
	v_rcp_f32_e32 v64, v64
	s_nop 0
	v_mul_f32_e32 v3, v3, v64
	v_mul_f32_e32 v64, v2, v3
	v_pk_fma_f32 v[2:3], v[18:19], v[88:89], v[34:35]
	s_nop 0
	v_pk_fma_f32 v[2:3], v[10:11], v[76:77], v[2:3]
	v_and_b32_e32 v77, 0xffff0000, v62
	v_pk_fma_f32 v[2:3], v[26:27], v[84:85], v[2:3]
	v_and_b32_e32 v76, 0xffff0000, v66
	s_nop 0
	v_mul_f32_e32 v61, 0xbdd2d3e7, v3
	v_fmaak_f32 v61, v3, v61, 0xc0135761
	v_mul_f32_e32 v61, v3, v61
	v_exp_f32_e32 v61, v61
	s_nop 0
	v_add_f32_e32 v61, 1.0, v61
	v_rcp_f32_e32 v61, v61
	s_nop 0
	v_mul_f32_e32 v3, v3, v61
	v_mul_f32_e32 v61, v2, v3
	v_pk_fma_f32 v[2:3], v[132:133], v[100:101], v[128:129]
; __device__ __forceinline__ unsigned cvt_pk_bf16(float lo, float hi) { unsigned r; asm volatile("v_cvt_pk_bf16_f32 %0, %1, %2" : "=v"(r) : "v"(lo), "v"(hi)); return r; }
; __device__ __forceinline__ void ffnconv_phase(const bf16* h, bf16* gout, const float* cw, const float* cb, int T, int vcu, int NT) {
;     ...
;             for (int q = 0; q < RS; ++q) {
;                 const int tpos = (t + q) & (T - 1);
;                 const float mp = tpos == 0 ? 0.f : 1.f, mn = tpos == T - 1 ? 0.f : 1.f;
;                 float a0[8], a1[8], a2[8], b0[8], b1[8], b2[8], r[8];
;                 unpack8(gp_, a0); unpack8(gc_, a1); unpack8(gn_[q], a2); unpack8(vp_, b0); unpack8(vc_, b1); unpack8(vn_[q], b2);
; #pragma unroll
;                 for (int e = 0; e < 8; ++e) { const float hg = wg0[e] * (a0[e] * mp) + wg1[e] * a1[e] + wg2[e] * (a2[e] * mn) + bg[e];
;                     const float hv = wv0[e] * (b0[e] * mp) + wv1[e] * b1[e] + wv2[e] * (b2[e] * mn) + bv[e]; r[e] = gelu_tanh(hg) * hv; }
;                 v4u o; o.x = cvt_pk_bf16(r[0], r[1]); o.y = cvt_pk_bf16(r[2], r[3]); o.z = cvt_pk_bf16(r[4], r[5]); o.w = cvt_pk_bf16(r[6], r[7]);
;                 *(v4u*)(gout + (size_t)(t + q) * DFF + ch) = o;
	v_cvt_pk_bf16_f32 v61, v64, v61
	v_lshlrev_b32_e32 v64, 16, v57
	v_pk_fma_f32 v[2:3], v[130:131], v[108:109], v[2:3]
	s_nop 0
	v_pk_fma_f32 v[2:3], v[134:135], v[90:91], v[2:3]
	s_nop 0
	s_nop 0
	v_mul_f32_e32 v65, 0xbdd2d3e7, v3
	v_fmaak_f32 v65, v3, v65, 0xc0135761
	v_mul_f32_e32 v65, v3, v65
	v_exp_f32_e32 v65, v65
	s_nop 0
	v_add_f32_e32 v65, 1.0, v65
	v_rcp_f32_e32 v65, v65
	s_nop 0
	v_mul_f32_e32 v3, v3, v65
	v_mul_f32_e32 v65, v2, v3
	v_pk_fma_f32 v[2:3], v[12:13], v[72:73], v[28:29]
	s_nop 0
	v_pk_fma_f32 v[2:3], v[4:5], v[80:81], v[2:3]
	v_and_b32_e32 v81, 0xffff0000, v63
	v_pk_fma_f32 v[2:3], v[20:21], v[76:77], v[2:3]
	v_and_b32_e32 v80, 0xffff0000, v67
	v_and_b32_e32 v67, 0xffff0000, v52
	v_mul_f32_e32 v62, 0xbdd2d3e7, v3
	v_fmaak_f32 v62, v3, v62, 0xc0135761
	v_mul_f32_e32 v62, v3, v62
	v_exp_f32_e32 v62, v62
	s_nop 0
	v_add_f32_e32 v62, 1.0, v62
	v_rcp_f32_e32 v62, v62
	s_nop 0
	v_mul_f32_e32 v3, v3, v62
	v_mul_f32_e32 v62, v2, v3
	v_pk_fma_f32 v[2:3], v[124:125], v[96:97], v[120:121]
	v_cvt_pk_bf16_f32 v62, v65, v62
	v_lshlrev_b32_e32 v65, 16, v53
	v_pk_fma_f32 v[2:3], v[122:123], v[106:107], v[2:3]
	s_nop 0
	v_pk_fma_f32 v[2:3], v[126:127], v[86:87], v[2:3]
	s_nop 0
	s_nop 0
	v_mul_f32_e32 v66, 0xbdd2d3e7, v3
	v_fmaak_f32 v66, v3, v66, 0xc0135761
	v_mul_f32_e32 v66, v3, v66
	v_exp_f32_e32 v66, v66
	s_nop 0
	v_add_f32_e32 v66, 1.0, v66
	v_rcp_f32_e32 v66, v66
	s_nop 0
	v_mul_f32_e32 v3, v3, v66
	v_mul_f32_e32 v66, v2, v3
	v_pk_fma_f32 v[2:3], v[14:15], v[70:71], v[30:31]
	s_nop 0
	v_pk_fma_f32 v[2:3], v[6:7], v[78:79], v[2:3]
	s_nop 0
	v_pk_fma_f32 v[2:3], v[22:23], v[80:81], v[2:3]
	s_nop 0
	s_nop 0
	v_mul_f32_e32 v63, 0xbdd2d3e7, v3
	v_fmaak_f32 v63, v3, v63, 0xc0135761
	v_mul_f32_e32 v63, v3, v63
	v_exp_f32_e32 v63, v63
	s_nop 0
	v_add_f32_e32 v63, 1.0, v63
	v_rcp_f32_e32 v63, v63
	s_nop 0
	v_mul_f32_e32 v3, v3, v63
	v_mul_f32_e32 v2, v2, v3
	v_cvt_pk_bf16_f32 v63, v66, v2
	v_mad_i64_i32 v[2:3], s[24:25], v214, s84, v[118:119]
	global_store_dwordx4 v[2:3], v[60:63], off
	v_pk_fma_f32 v[2:3], v[148:149], v[94:95], v[144:145]
	v_and_b32_e32 v66, 0xffff0000, v56
	v_pk_fma_f32 v[2:3], v[146:147], v[104:105], v[2:3]
	v_and_b32_e32 v63, 0xffff0000, v53
	v_pk_fma_f32 v[2:3], v[150:151], v[68:69], v[2:3]
	v_and_b32_e32 v62, 0xffff0000, v57
	v_lshlrev_b32_e32 v61, 16, v54
	v_mul_f32_e32 v60, 0xbdd2d3e7, v3
	v_fmaak_f32 v60, v3, v60, 0xc0135761
	v_mul_f32_e32 v60, v3, v60
	v_exp_f32_e32 v60, v60
	v_and_b32_e32 v57, 0xffff0000, v54
	v_and_b32_e32 v56, 0xffff0000, v58
	v_lshlrev_b32_e32 v53, 16, v55
	v_add_f32_e32 v60, 1.0, v60
	v_rcp_f32_e32 v60, v60
	s_nop 0
	v_mul_f32_e32 v3, v3, v60
	v_mul_f32_e32 v78, v2, v3
	v_pk_fma_f32 v[2:3], v[16:17], v[74:75], v[32:33]
	v_lshlrev_b32_e32 v60, 16, v58
	v_pk_fma_f32 v[2:3], v[8:9], v[82:83], v[2:3]
	s_nop 0
	v_pk_fma_f32 v[2:3], v[24:25], v[66:67], v[2:3]
	s_nop 0
	s_nop 0
	v_mul_f32_e32 v52, 0xbdd2d3e7, v3
	v_fmaak_f32 v52, v3, v52, 0xc0135761
	v_mul_f32_e32 v52, v3, v52
	v_exp_f32_e32 v52, v52
	s_nop 0
	v_add_f32_e32 v52, 1.0, v52
	v_rcp_f32_e32 v52, v52
	s_nop 0
	v_mul_f32_e32 v3, v3, v52
	v_mul_f32_e32 v79, v2, v3
	v_pk_fma_f32 v[2:3], v[140:141], v[92:93], v[136:137]
	s_nop 0
	v_pk_fma_f32 v[2:3], v[138:139], v[102:103], v[2:3]
	v_mov_b32_e32 v102, v42
	v_pk_fma_f32 v[2:3], v[142:143], v[64:65], v[2:3]
	v_mov_b32_e32 v103, v43
	s_nop 0
	v_mul_f32_e32 v52, 0xbdd2d3e7, v3
	v_fmaak_f32 v52, v3, v52, 0xc0135761
	v_mul_f32_e32 v52, v3, v52
	v_exp_f32_e32 v52, v52
	s_nop 0
	v_add_f32_e32 v52, 1.0, v52
	v_rcp_f32_e32 v52, v52
	s_nop 0
	v_mul_f32_e32 v3, v3, v52
	v_mul_f32_e32 v82, v2, v3
	v_pk_fma_f32 v[2:3], v[18:19], v[84:85], v[34:35]
	s_nop 0
	v_pk_fma_f32 v[2:3], v[10:11], v[88:89], v[2:3]
	v_lshlrev_b32_e32 v89, 16, v36
	v_pk_fma_f32 v[2:3], v[26:27], v[62:63], v[2:3]
	s_nop 0
	s_nop 0
	v_mul_f32_e32 v52, 0xbdd2d3e7, v3
	v_fmaak_f32 v52, v3, v52, 0xc0135761
	v_mul_f32_e32 v52, v3, v52
	v_exp_f32_e32 v52, v52
	s_nop 0
	v_add_f32_e32 v52, 1.0, v52
	v_rcp_f32_e32 v52, v52
	s_nop 0
	v_mul_f32_e32 v3, v3, v52
	v_mul_f32_e32 v83, v2, v3
	v_pk_fma_f32 v[2:3], v[132:133], v[90:91], v[128:129]
	s_nop 0
	v_pk_fma_f32 v[2:3], v[130:131], v[100:101], v[2:3]
	v_mov_b32_e32 v100, v40
	v_pk_fma_f32 v[2:3], v[134:135], v[60:61], v[2:3]
	v_mov_b32_e32 v101, v41
	s_nop 0
	v_mul_f32_e32 v52, 0xbdd2d3e7, v3
	v_fmaak_f32 v52, v3, v52, 0xc0135761
	v_mul_f32_e32 v52, v3, v52
	v_exp_f32_e32 v52, v52
	s_nop 0
	v_add_f32_e32 v52, 1.0, v52
	v_rcp_f32_e32 v52, v52
	s_nop 0
	v_mul_f32_e32 v3, v3, v52
	v_mul_f32_e32 v88, v2, v3
	v_pk_fma_f32 v[2:3], v[12:13], v[76:77], v[28:29]
	s_nop 0
	v_pk_fma_f32 v[2:3], v[4:5], v[72:73], v[2:3]
	s_nop 0
	v_pk_fma_f32 v[2:3], v[20:21], v[56:57], v[2:3]
	s_nop 0
	s_nop 0
	v_mul_f32_e32 v52, 0xbdd2d3e7, v3
	v_fmaak_f32 v52, v3, v52, 0xc0135761
	v_mul_f32_e32 v52, v3, v52
	v_exp_f32_e32 v52, v52
	s_nop 0
	v_add_f32_e32 v52, 1.0, v52
	v_rcp_f32_e32 v52, v52
	s_nop 0
	v_mul_f32_e32 v3, v3, v52
	v_mul_f32_e32 v58, v2, v3
	v_pk_fma_f32 v[2:3], v[124:125], v[86:87], v[120:121]
	v_lshlrev_b32_e32 v52, 16, v59
	v_pk_fma_f32 v[2:3], v[122:123], v[96:97], v[2:3]
	v_mov_b32_e32 v96, v36
	v_pk_fma_f32 v[2:3], v[126:127], v[52:53], v[2:3]
	v_mov_b32_e32 v97, v37
	s_nop 0
	v_mul_f32_e32 v54, 0xbdd2d3e7, v3
	v_fmaak_f32 v54, v3, v54, 0xc0135761
	v_mul_f32_e32 v54, v3, v54
	v_exp_f32_e32 v54, v54
	s_nop 0
	v_add_f32_e32 v54, 1.0, v54
	v_rcp_f32_e32 v54, v54
	s_nop 0
	v_mul_f32_e32 v3, v3, v54
	v_mul_f32_e32 v73, v2, v3
	v_and_b32_e32 v3, 0xffff0000, v55
	v_pk_fma_f32 v[54:55], v[14:15], v[80:81], v[30:31]
	v_and_b32_e32 v2, 0xffff0000, v59
	v_pk_fma_f32 v[54:55], v[6:7], v[70:71], v[54:55]
; __device__ __forceinline__ unsigned cvt_pk_bf16(float lo, float hi) { unsigned r; asm volatile("v_cvt_pk_bf16_f32 %0, %1, %2" : "=v"(r) : "v"(lo), "v"(hi)); return r; }
; __device__ __forceinline__ void ffnconv_phase(const bf16* h, bf16* gout, const float* cw, const float* cb, int T, int vcu, int NT) {
;     ...
;             for (int q = 0; q < RS; ++q) {
;                 const int tpos = (t + q) & (T - 1);
;                 const float mp = tpos == 0 ? 0.f : 1.f, mn = tpos == T - 1 ? 0.f : 1.f;
;                 float a0[8], a1[8], a2[8], b0[8], b1[8], b2[8], r[8];
;                 unpack8(gp_, a0); unpack8(gc_, a1); unpack8(gn_[q], a2); unpack8(vp_, b0); unpack8(vc_, b1); unpack8(vn_[q], b2);
; #pragma unroll
;                 for (int e = 0; e < 8; ++e) { const float hg = wg0[e] * (a0[e] * mp) + wg1[e] * a1[e] + wg2[e] * (a2[e] * mn) + bg[e];
;                     const float hv = wv0[e] * (b0[e] * mp) + wv1[e] * b1[e] + wv2[e] * (b2[e] * mn) + bv[e]; r[e] = gelu_tanh(hg) * hv; }
;                 v4u o; o.x = cvt_pk_bf16(r[0], r[1]); o.y = cvt_pk_bf16(r[2], r[3]); o.z = cvt_pk_bf16(r[4], r[5]); o.w = cvt_pk_bf16(r[6], r[7]);
;                 *(v4u*)(gout + (size_t)(t + q) * DFF + ch) = o;
;                 gp_ = gc_; gc_ = gn_[q]; vp_ = vc_; vc_ = vn_[q]; }
	v_cvt_pk_bf16_f32 v70, v78, v79
	v_cvt_pk_bf16_f32 v71, v82, v83
	v_cvt_pk_bf16_f32 v72, v88, v58
	v_lshlrev_b32_e32 v88, 16, v40
	v_pk_fma_f32 v[54:55], v[22:23], v[2:3], v[54:55]
	v_and_b32_e32 v83, 0xffff0000, v36
	v_and_b32_e32 v82, 0xffff0000, v40
	v_mul_f32_e32 v59, 0xbdd2d3e7, v55
	v_fmaak_f32 v59, v55, v59, 0xc0135761
	v_mul_f32_e32 v59, v55, v59
	v_exp_f32_e32 v59, v59
	v_lshlrev_b32_e32 v78, 16, v41
	v_lshlrev_b32_e32 v79, 16, v37
	v_add_f32_e32 v59, 1.0, v59
	v_rcp_f32_e32 v59, v59
	s_nop 0
	v_mul_f32_e32 v55, v55, v59
	v_mul_f32_e32 v54, v54, v55
	v_cvt_pk_bf16_f32 v73, v73, v54
	v_mad_i64_i32 v[54:55], s[24:25], v213, s84, v[118:119]
	global_store_dwordx4 v[54:55], v[70:73], off
	v_pk_fma_f32 v[54:55], v[148:149], v[68:69], v[144:145]
	v_lshlrev_b32_e32 v59, 16, v39
	v_pk_fma_f32 v[54:55], v[146:147], v[94:95], v[54:55]
	v_lshlrev_b32_e32 v73, 16, v38
	v_pk_fma_f32 v[54:55], v[150:151], v[88:89], v[54:55]
	v_lshlrev_b32_e32 v72, 16, v42
	v_and_b32_e32 v71, 0xffff0000, v38
	v_mul_f32_e32 v58, 0xbdd2d3e7, v55
	v_fmaak_f32 v58, v55, v58, 0xc0135761
	v_mul_f32_e32 v58, v55, v58
	v_exp_f32_e32 v58, v58
	v_and_b32_e32 v70, 0xffff0000, v42
	v_add_f32_e32 v58, 1.0, v58
	v_rcp_f32_e32 v58, v58
	s_nop 0
	v_mul_f32_e32 v55, v55, v58
	v_mul_f32_e32 v94, v54, v55
	v_pk_fma_f32 v[54:55], v[16:17], v[66:67], v[32:33]
	s_nop 0
	v_pk_fma_f32 v[54:55], v[8:9], v[74:75], v[54:55]
	v_and_b32_e32 v75, 0xffff0000, v37
	v_pk_fma_f32 v[54:55], v[24:25], v[82:83], v[54:55]
	v_and_b32_e32 v74, 0xffff0000, v41
	s_nop 0
	v_mul_f32_e32 v58, 0xbdd2d3e7, v55
	v_fmaak_f32 v58, v55, v58, 0xc0135761
	v_mul_f32_e32 v58, v55, v58
	v_exp_f32_e32 v58, v58
	s_nop 0
	v_add_f32_e32 v58, 1.0, v58
	v_rcp_f32_e32 v58, v58
	s_nop 0
	v_mul_f32_e32 v55, v55, v58
	v_mul_f32_e32 v95, v54, v55
	v_pk_fma_f32 v[54:55], v[140:141], v[64:65], v[136:137]
	s_nop 0
	v_pk_fma_f32 v[54:55], v[138:139], v[92:93], v[54:55]
	s_nop 0
	v_pk_fma_f32 v[54:55], v[142:143], v[78:79], v[54:55]
	s_nop 0
	s_nop 0
	v_mul_f32_e32 v58, 0xbdd2d3e7, v55
	v_fmaak_f32 v58, v55, v58, 0xc0135761
	v_mul_f32_e32 v58, v55, v58
	v_exp_f32_e32 v58, v58
	s_nop 0
	v_add_f32_e32 v58, 1.0, v58
	v_rcp_f32_e32 v58, v58
	s_nop 0
	v_mul_f32_e32 v55, v55, v58
	v_mul_f32_e32 v92, v54, v55
	v_pk_fma_f32 v[54:55], v[18:19], v[62:63], v[34:35]
	s_nop 0
	v_pk_fma_f32 v[54:55], v[10:11], v[84:85], v[54:55]
	v_cvt_pk_bf16_f32 v84, v94, v95
	s_nop 0
	v_pk_fma_f32 v[54:55], v[26:27], v[74:75], v[54:55]
	s_nop 0
	s_nop 0
	v_mul_f32_e32 v58, 0xbdd2d3e7, v55
	v_fmaak_f32 v58, v55, v58, 0xc0135761
	v_mul_f32_e32 v58, v55, v58
	v_exp_f32_e32 v58, v58
	s_nop 0
	v_add_f32_e32 v58, 1.0, v58
	v_rcp_f32_e32 v58, v58
	s_nop 0
	v_mul_f32_e32 v55, v55, v58
	v_mul_f32_e32 v85, v54, v55
	v_pk_fma_f32 v[54:55], v[132:133], v[60:61], v[128:129]
	v_cvt_pk_bf16_f32 v85, v92, v85
	v_mov_b64_e32 v[94:95], v[50:51]
	v_pk_fma_f32 v[54:55], v[130:131], v[90:91], v[54:55]
	v_mov_b64_e32 v[92:93], v[48:49]
	v_pk_fma_f32 v[54:55], v[134:135], v[72:73], v[54:55]
	s_nop 0
	s_nop 0
	v_mul_f32_e32 v58, 0xbdd2d3e7, v55
	v_fmaak_f32 v58, v55, v58, 0xc0135761
	v_mul_f32_e32 v58, v55, v58
	v_exp_f32_e32 v58, v58
	s_nop 0
	v_add_f32_e32 v58, 1.0, v58
	v_rcp_f32_e32 v58, v58
	s_nop 0
	v_mul_f32_e32 v55, v55, v58
	v_mul_f32_e32 v90, v54, v55
	v_pk_fma_f32 v[54:55], v[12:13], v[56:57], v[28:29]
	s_nop 0
	v_pk_fma_f32 v[54:55], v[4:5], v[76:77], v[54:55]
	s_nop 0
	v_pk_fma_f32 v[54:55], v[20:21], v[70:71], v[54:55]
	s_nop 0
	s_nop 0
	v_mul_f32_e32 v58, 0xbdd2d3e7, v55
	v_fmaak_f32 v58, v55, v58, 0xc0135761
	v_mul_f32_e32 v58, v55, v58
	v_exp_f32_e32 v58, v58
	s_nop 0
	v_add_f32_e32 v58, 1.0, v58
	v_rcp_f32_e32 v58, v58
	s_nop 0
	v_mul_f32_e32 v55, v55, v58
	v_mul_f32_e32 v91, v54, v55
	v_pk_fma_f32 v[54:55], v[124:125], v[52:53], v[120:121]
	v_lshlrev_b32_e32 v58, 16, v43
	v_pk_fma_f32 v[54:55], v[122:123], v[86:87], v[54:55]
	v_cvt_pk_bf16_f32 v86, v90, v91
	s_nop 0
	v_pk_fma_f32 v[54:55], v[126:127], v[58:59], v[54:55]
	v_pk_fma_f32 v[58:59], v[124:125], v[58:59], v[120:121]
	v_pk_fma_f32 v[52:53], v[122:123], v[52:53], v[58:59]
	v_mul_f32_e32 v76, 0xbdd2d3e7, v55
	v_fmaak_f32 v76, v55, v76, 0xc0135761
	v_mul_f32_e32 v76, v55, v76
	v_exp_f32_e32 v76, v76
	s_nop 0
	v_add_f32_e32 v76, 1.0, v76
	v_rcp_f32_e32 v76, v76
	s_nop 0
	v_mul_f32_e32 v55, v55, v76
	v_pk_fma_f32 v[76:77], v[14:15], v[2:3], v[30:31]
	v_mul_f32_e32 v87, v54, v55
	v_and_b32_e32 v55, 0xffff0000, v39
	v_and_b32_e32 v54, 0xffff0000, v43
	v_pk_fma_f32 v[76:77], v[6:7], v[80:81], v[76:77]
	v_lshlrev_b32_e32 v81, 16, v44
	v_pk_fma_f32 v[76:77], v[22:23], v[54:55], v[76:77]
	v_pk_fma_f32 v[54:55], v[14:15], v[54:55], v[30:31]
	v_pk_fma_f32 v[2:3], v[6:7], v[2:3], v[54:55]
	v_mul_f32_e32 v80, 0xbdd2d3e7, v77
	v_fmaak_f32 v80, v77, v80, 0xc0135761
	v_mul_f32_e32 v80, v77, v80
	v_exp_f32_e32 v80, v80
	s_nop 0
	v_add_f32_e32 v80, 1.0, v80
	v_rcp_f32_e32 v80, v80
	s_nop 0
	v_mul_f32_e32 v77, v77, v80
	v_mul_f32_e32 v76, v76, v77
	v_cvt_pk_bf16_f32 v87, v87, v76
; __device__ __forceinline__ unsigned cvt_pk_bf16(float lo, float hi) { unsigned r; asm volatile("v_cvt_pk_bf16_f32 %0, %1, %2" : "=v"(r) : "v"(lo), "v"(hi)); return r; }
; __device__ __forceinline__ void ffnconv_phase(const bf16* h, bf16* gout, const float* cw, const float* cb, int T, int vcu, int NT) {
;     ...
;         for (int t = t0; t < t1; t += RS) {
;     ...
;             for (int q = 0; q < RS; ++q) {
;                 const int tpos = (t + q) & (T - 1);
;                 const float mp = tpos == 0 ? 0.f : 1.f, mn = tpos == T - 1 ? 0.f : 1.f;
;                 float a0[8], a1[8], a2[8], b0[8], b1[8], b2[8], r[8];
;                 unpack8(gp_, a0); unpack8(gc_, a1); unpack8(gn_[q], a2); unpack8(vp_, b0); unpack8(vc_, b1); unpack8(vn_[q], b2);
; #pragma unroll
;                 for (int e = 0; e < 8; ++e) { const float hg = wg0[e] * (a0[e] * mp) + wg1[e] * a1[e] + wg2[e] * (a2[e] * mn) + bg[e];
;                     const float hv = wv0[e] * (b0[e] * mp) + wv1[e] * b1[e] + wv2[e] * (b2[e] * mn) + bv[e]; r[e] = gelu_tanh(hg) * hv; }
;                 v4u o; o.x = cvt_pk_bf16(r[0], r[1]); o.y = cvt_pk_bf16(r[2], r[3]); o.z = cvt_pk_bf16(r[4], r[5]); o.w = cvt_pk_bf16(r[6], r[7]);
;                 *(v4u*)(gout + (size_t)(t + q) * DFF + ch) = o;
;                 gp_ = gc_; gc_ = gn_[q]; vp_ = vc_; vc_ = vn_[q]; }
;             p += RS * (size_t)NUP;
	v_mad_i64_i32 v[76:77], s[24:25], v1, s84, v[118:119]
	v_and_b32_e32 v1, s88, v212
	v_cmp_eq_u32_e32 vcc, s88, v1
	global_store_dwordx4 v[76:77], v[84:87], off
	v_lshlrev_b32_e32 v80, 16, v48
	v_cndmask_b32_e64 v76, 1.0, 0, vcc
	v_pk_fma_f32 v[84:85], v[148:149], v[88:89], v[144:145]
	v_pk_mul_f32 v[80:81], v[76:77], v[80:81] op_sel_hi:[0,1]
	v_pk_fma_f32 v[68:69], v[146:147], v[68:69], v[84:85]
	v_mov_b64_e32 v[90:91], v[46:47]
	v_pk_fma_f32 v[68:69], v[150:151], v[80:81], v[68:69]
	v_pk_fma_f32 v[80:81], v[16:17], v[82:83], v[32:33]
	v_pk_fma_f32 v[66:67], v[8:9], v[66:67], v[80:81]
	v_mul_f32_e32 v1, 0xbdd2d3e7, v69
	v_fmaak_f32 v1, v69, v1, 0xc0135761
	v_mul_f32_e32 v1, v69, v1
	v_exp_f32_e32 v1, v1
	v_mov_b64_e32 v[88:89], v[44:45]
	v_add_f32_e32 v1, 1.0, v1
	v_rcp_f32_e32 v1, v1
	s_nop 0
	v_mul_f32_e32 v1, v69, v1
	v_mul_f32_e32 v1, v68, v1
	v_and_b32_e32 v69, 0xffff0000, v44
	v_and_b32_e32 v68, 0xffff0000, v48
	v_pk_mul_f32 v[68:69], v[76:77], v[68:69] op_sel_hi:[0,1]
	v_pk_fma_f32 v[66:67], v[24:25], v[68:69], v[66:67]
	s_nop 0
	s_nop 0
	v_mul_f32_e32 v68, 0xbdd2d3e7, v67
	v_fmaak_f32 v68, v67, v68, 0xc0135761
	v_mul_f32_e32 v68, v67, v68
	v_exp_f32_e32 v68, v68
	s_nop 0
	v_add_f32_e32 v68, 1.0, v68
	v_rcp_f32_e32 v68, v68
	s_nop 0
	v_mul_f32_e32 v67, v67, v68
	v_mul_f32_e32 v77, v66, v67
	v_lshlrev_b32_e32 v67, 16, v45
	v_lshlrev_b32_e32 v66, 16, v49
	v_pk_fma_f32 v[68:69], v[140:141], v[78:79], v[136:137]
	v_pk_mul_f32 v[66:67], v[76:77], v[66:67] op_sel_hi:[0,1]
	v_pk_fma_f32 v[64:65], v[138:139], v[64:65], v[68:69]
	s_nop 0
	v_pk_fma_f32 v[64:65], v[142:143], v[66:67], v[64:65]
	s_nop 0
	s_nop 0
	v_mul_f32_e32 v66, 0xbdd2d3e7, v65
	v_fmaak_f32 v66, v65, v66, 0xc0135761
	v_mul_f32_e32 v66, v65, v66
	v_exp_f32_e32 v66, v66
	s_nop 0
	v_add_f32_e32 v66, 1.0, v66
	v_rcp_f32_e32 v66, v66
	s_nop 0
	v_mul_f32_e32 v65, v65, v66
	v_mul_f32_e32 v68, v64, v65
	v_and_b32_e32 v65, 0xffff0000, v45
	v_and_b32_e32 v64, 0xffff0000, v49
	v_pk_fma_f32 v[66:67], v[18:19], v[74:75], v[34:35]
	v_pk_mul_f32 v[64:65], v[76:77], v[64:65] op_sel_hi:[0,1]
	v_pk_fma_f32 v[62:63], v[10:11], v[62:63], v[66:67]
	s_nop 0
	v_pk_fma_f32 v[62:63], v[26:27], v[64:65], v[62:63]
	s_nop 0
	s_nop 0
	v_mul_f32_e32 v64, 0xbdd2d3e7, v63
	v_fmaak_f32 v64, v63, v64, 0xc0135761
	v_mul_f32_e32 v64, v63, v64
	v_exp_f32_e32 v64, v64
	s_nop 0
	v_add_f32_e32 v64, 1.0, v64
	v_rcp_f32_e32 v64, v64
	s_nop 0
	v_mul_f32_e32 v63, v63, v64
	v_mul_f32_e32 v66, v62, v63
	v_lshlrev_b32_e32 v63, 16, v46
	v_lshlrev_b32_e32 v62, 16, v50
	v_pk_fma_f32 v[64:65], v[132:133], v[72:73], v[128:129]
	v_pk_mul_f32 v[62:63], v[76:77], v[62:63] op_sel_hi:[0,1]
	v_pk_fma_f32 v[60:61], v[130:131], v[60:61], v[64:65]
	s_nop 0
	v_pk_fma_f32 v[60:61], v[134:135], v[62:63], v[60:61]
	s_nop 0
	s_nop 0
	v_mul_f32_e32 v62, 0xbdd2d3e7, v61
	v_fmaak_f32 v62, v61, v62, 0xc0135761
	v_mul_f32_e32 v62, v61, v62
	v_exp_f32_e32 v62, v62
	s_nop 0
	v_add_f32_e32 v62, 1.0, v62
	v_rcp_f32_e32 v62, v62
	s_nop 0
	v_mul_f32_e32 v61, v61, v62
	v_mul_f32_e32 v64, v60, v61
	v_and_b32_e32 v61, 0xffff0000, v46
	v_and_b32_e32 v60, 0xffff0000, v50
	v_pk_fma_f32 v[62:63], v[12:13], v[70:71], v[28:29]
	v_pk_mul_f32 v[60:61], v[76:77], v[60:61] op_sel_hi:[0,1]
	v_pk_fma_f32 v[56:57], v[4:5], v[56:57], v[62:63]
	s_nop 0
	v_pk_fma_f32 v[56:57], v[20:21], v[60:61], v[56:57]
	s_nop 0
	s_nop 0
	v_mul_f32_e32 v60, 0xbdd2d3e7, v57
	v_fmaak_f32 v60, v57, v60, 0xc0135761
	v_mul_f32_e32 v60, v57, v60
	v_exp_f32_e32 v60, v60
	s_nop 0
	v_add_f32_e32 v60, 1.0, v60
	v_rcp_f32_e32 v60, v60
	s_nop 0
	v_mul_f32_e32 v57, v57, v60
	v_mul_f32_e32 v60, v56, v57
	v_lshlrev_b32_e32 v57, 16, v47
	v_lshlrev_b32_e32 v56, 16, v51
	v_pk_mul_f32 v[56:57], v[76:77], v[56:57] op_sel_hi:[0,1]
	v_pk_fma_f32 v[52:53], v[126:127], v[56:57], v[52:53]
	s_nop 0
	s_nop 0
	v_mul_f32_e32 v56, 0xbdd2d3e7, v53
	v_fmaak_f32 v56, v53, v56, 0xc0135761
	v_mul_f32_e32 v56, v53, v56
	v_exp_f32_e32 v56, v56
	s_nop 0
	v_add_f32_e32 v56, 1.0, v56
	v_rcp_f32_e32 v56, v56
	s_nop 0
	v_mul_f32_e32 v53, v53, v56
	v_mul_f32_e32 v56, v52, v53
	v_and_b32_e32 v53, 0xffff0000, v47
	v_and_b32_e32 v52, 0xffff0000, v51
	v_pk_mul_f32 v[52:53], v[76:77], v[52:53] op_sel_hi:[0,1]
	v_pk_fma_f32 v[2:3], v[22:23], v[52:53], v[2:3]
	s_nop 0
	s_nop 0
	v_mul_f32_e32 v52, 0xbdd2d3e7, v3
	v_fmaak_f32 v52, v3, v52, 0xc0135761
	v_mul_f32_e32 v52, v3, v52
	v_exp_f32_e32 v52, v52
	s_nop 0
	v_add_f32_e32 v52, 1.0, v52
	v_rcp_f32_e32 v52, v52
	s_nop 0
	v_mul_f32_e32 v3, v3, v52
	v_mul_f32_e32 v2, v2, v3
	v_cvt_pk_bf16_f32 v52, v1, v77
	v_cvt_pk_bf16_f32 v53, v68, v66
	v_cvt_pk_bf16_f32 v54, v64, v60
	v_cvt_pk_bf16_f32 v55, v56, v2
	v_mad_i64_i32 v[2:3], s[24:25], v211, s84, v[118:119]
	v_add_u32_e32 v1, 1, v212
	s_mov_b64 s[24:25], 0xb000
	v_cmp_ge_i32_e32 vcc, v1, v210
	v_lshl_add_u64 v[190:191], v[190:191], 0, s[24:25]
	v_add_u32_e32 v211, 8, v211
	s_or_b64 s[60:61], vcc, s[60:61]
	global_store_dwordx4 v[2:3], v[52:55], off
	s_andn2_b64 exec, exec, s[60:61]
	s_cbranch_execz .LBB0_876
